# P5 attention unit epilogue: the 16 gate loads issued together behind the first (dead registers), counted vmcnt(14) per output tile instead of a load-wait chain
# baseline (speedup 1.0000x reference)
; #define GAS __attribute__((address_space(1)))
; __device__ __forceinline__ unsigned pk2(float lo, float hi) { return pg8::cvt_pk_bf16(lo, hi); }
; __device__ __forceinline__ float fexp2(float x) { return __builtin_amdgcn_exp2f(x); }
; __device__ __forceinline__ float siluf_(float x) { return x * sigmoidf_(x); }
; __device__ __forceinline__ void attn_unit(const Args& a, LAS unsigned char* lds, int unit, int tid, int lane, int wave) {
;     ...
;     for (int qt = 0; qt < 2; ++qt) {
;         float L = lpart[qt]; L += __shfl_xor(L, 16); L += __shfl_xor(L, 32);
;         L += fexp2(sinkl2 - mrun[qt]);
;         const float inv = 1.0f / L;
;         const size_t row = (size_t)b * SEQ + nblk * 128 + qoff + 16 * qt + c16;
; #pragma unroll
;         for (int dt = 0; dt < 8; ++dt) {
;             const int d = 16 * dt + 4 * g;
;             const v2u gw = *(const GAS v2u*)(Z + row * ZLD + ZGA + hq * 128 + d);
;             const float g0 = bflo(gw.x), g1 = bfhi(gw.x), g2 = bflo(gw.y), g3 = bfhi(gw.y);
;             v2u w; w.x = pk2(O[qt][dt][0] * inv * siluf_(g0), O[qt][dt][1] * inv * siluf_(g1)); w.y = pk2(O[qt][dt][2] * inv * siluf_(g2), O[qt][dt][3] * inv * siluf_(g3));
;             *(GAS v2u*)(OAB + row * D + hq * 128 + d) = w;
;         }
;     }
.LBB0_640:
	s_lshl_b64 s[0:1], s[10:11], 1
	v_lshl_add_u64 v[62:63], s[50:51], 0, v[166:167]
	v_mov_b32_e32 v161, v149
	v_lshl_add_u64 v[62:63], v[62:63], 0, s[0:1]
	v_lshl_add_u64 v[62:63], v[62:63], 0, v[160:161]
	v_add_co_u32_e32 v64, vcc, s23, v62
	v_and_b32_e32 v67, 64, v184
	s_nop 0
	v_addc_co_u32_e32 v65, vcc, 0, v63, vcc
	v_mov_b64_e32 v[224:225], v[64:65]
	global_load_dwordx2 v[64:65], v[64:65], off offset:2048
	v_add_co_u32_e32 v226, vcc, 0x6c000, v224
	s_nop 1
	v_addc_co_u32_e32 v227, vcc, 0, v225, vcc
	global_load_dwordx2 v[194:195], v[224:225], off offset:2080
	global_load_dwordx2 v[196:197], v[224:225], off offset:2112
	global_load_dwordx2 v[198:199], v[224:225], off offset:2144
	global_load_dwordx2 v[200:201], v[224:225], off offset:2176
	global_load_dwordx2 v[202:203], v[224:225], off offset:2208
	global_load_dwordx2 v[204:205], v[224:225], off offset:2240
	global_load_dwordx2 v[206:207], v[224:225], off offset:2272
	global_load_dwordx2 v[208:209], v[226:227], off offset:2048
	global_load_dwordx2 v[210:211], v[226:227], off offset:2080
	global_load_dwordx2 v[212:213], v[226:227], off offset:2112
	global_load_dwordx2 v[214:215], v[226:227], off offset:2144
	global_load_dwordx2 v[216:217], v[226:227], off offset:2176
	global_load_dwordx2 v[218:219], v[226:227], off offset:2208
	global_load_dwordx2 v[220:221], v[226:227], off offset:2240
	global_load_dwordx2 v[222:223], v[226:227], off offset:2272
	v_xor_b32_e32 v66, 16, v184
	v_add_u32_e32 v67, 64, v67
	v_cmp_lt_i32_e32 vcc, v66, v67
	v_xor_b32_e32 v68, 32, v184
	v_sub_f32_e32 v69, v186, v190
	v_cndmask_b32_e32 v66, v184, v66, vcc
	v_lshlrev_b32_e32 v71, 2, v66
	ds_bpermute_b32 v66, v71, v189
	v_cmp_lt_i32_e32 vcc, v68, v67
	v_mov_b32_e32 v72, v110
	v_mov_b32_e32 v74, v111
	v_cndmask_b32_e32 v67, v184, v68, vcc
	v_lshlrev_b32_e32 v70, 2, v67
	s_waitcnt lgkmcnt(0)
	v_add_f32_e32 v66, v189, v66
	ds_bpermute_b32 v67, v70, v66
	v_exp_f32_e32 v68, v69
	v_mov_b32_e32 v76, v112
	v_mov_b32_e32 v78, v113
	s_mov_b64 s[4:5], 0x1800
	s_waitcnt lgkmcnt(0)
	v_add_f32_e32 v66, v66, v67
	v_add_f32_e32 v66, v68, v66
	v_div_scale_f32 v67, s[10:11], v66, v66, 1.0
	v_rcp_f32_e32 v73, v67
	v_div_scale_f32 v75, vcc, 1.0, v66, 1.0
	v_lshl_add_u64 v[68:69], v[62:63], 0, s[4:5]
	v_fma_f32 v77, -v67, v73, 1.0
	v_fmac_f32_e32 v73, v77, v73
	v_mul_f32_e32 v77, v75, v73
	v_fma_f32 v79, -v67, v77, v75
	v_fmac_f32_e32 v77, v79, v73
	v_fma_f32 v67, -v67, v77, v75
	v_div_fmas_f32 v67, v67, v73, v77
	v_div_fixup_f32 v66, v67, v66, 1.0
	s_add_u32 s0, s31, s0
	s_addc_u32 s1, s58, s1
	s_mov_b32 s4, 0x6d000
	s_add_i32 s25, s25, s16
	s_cmpk_gt_i32 s25, 0x3ff
	s_waitcnt vmcnt(15)
	v_lshlrev_b32_e32 v67, 16, v64
	v_and_b32_e32 v80, 0xffff0000, v64
	v_lshlrev_b32_e32 v81, 16, v65
	v_mul_f32_e32 v64, 0xbfb8aa3b, v67
	v_and_b32_e32 v82, 0xffff0000, v65
	v_mul_f32_e32 v65, 0xbfb8aa3b, v80
	v_mul_f32_e32 v73, 0xbfb8aa3b, v81
	v_exp_f32_e32 v64, v64
	v_mul_f32_e32 v75, 0xbfb8aa3b, v82
	v_exp_f32_e32 v65, v65
	v_exp_f32_e32 v73, v73
	v_exp_f32_e32 v75, v75
	v_add_f32_e32 v64, 1.0, v64
	v_add_f32_e32 v65, 1.0, v65
	v_add_f32_e32 v77, 1.0, v73
	v_rcp_f32_e32 v73, v64
	v_add_f32_e32 v79, 1.0, v75
	v_rcp_f32_e32 v75, v65
	v_rcp_f32_e32 v77, v77
	v_rcp_f32_e32 v79, v79
	v_pk_mul_f32 v[64:65], v[72:73], v[66:67]
	v_mov_b32_e32 v67, v80
	v_mul_f32_e32 v72, v64, v65
	v_pk_mul_f32 v[64:65], v[74:75], v[66:67]
	v_mov_b32_e32 v67, v81
	v_mul_f32_e32 v73, v64, v65
	v_pk_mul_f32 v[64:65], v[76:77], v[66:67]
	v_mov_b32_e32 v67, v82
	v_cvt_pk_bf16_f32 v72, v72, v73
	v_mul_f32_e32 v73, v64, v65
	v_pk_mul_f32 v[64:65], v[78:79], v[66:67]
	v_mov_b32_e32 v76, v58
	v_mul_f32_e32 v64, v64, v65
	v_cvt_pk_bf16_f32 v73, v73, v64
	s_waitcnt vmcnt(14)
	v_mov_b64_e32 v[74:75], v[194:195]
	v_lshlrev_b64 v[64:65], 13, v[162:163]
	v_mov_b32_e32 v78, v59
	v_lshl_add_u64 v[58:59], s[0:1], 0, v[64:65]
	v_mov_b32_e32 v80, v61
	v_lshl_add_u64 v[58:59], v[58:59], 0, v[160:161]
	global_store_dwordx2 v[58:59], v[72:73], off
	v_or_b32_e32 v64, 0x20000, v64
	s_nop 0
	v_lshlrev_b32_e32 v67, 16, v74
	v_and_b32_e32 v74, 0xffff0000, v74
	v_lshlrev_b32_e32 v82, 16, v75
	v_and_b32_e32 v75, 0xffff0000, v75
	v_mul_f32_e32 v61, 0xbfb8aa3b, v67
	v_mul_f32_e32 v72, 0xbfb8aa3b, v74
	v_mul_f32_e32 v77, 0xbfb8aa3b, v75
	v_exp_f32_e32 v61, v61
	v_mul_f32_e32 v73, 0xbfb8aa3b, v82
	v_exp_f32_e32 v72, v72
	v_exp_f32_e32 v77, v77
	v_exp_f32_e32 v73, v73
	v_add_f32_e32 v61, 1.0, v61
	v_add_f32_e32 v72, 1.0, v72
	v_add_f32_e32 v81, 1.0, v77
	v_rcp_f32_e32 v77, v61
	v_add_f32_e32 v73, 1.0, v73
	v_rcp_f32_e32 v79, v72
	v_rcp_f32_e32 v61, v73
	v_rcp_f32_e32 v81, v81
	v_pk_mul_f32 v[72:73], v[76:77], v[66:67]
	v_mov_b32_e32 v67, v74
	v_mul_f32_e32 v74, v72, v73
	v_pk_mul_f32 v[72:73], v[78:79], v[66:67]
	v_mov_b32_e32 v67, v82
	v_pk_mul_f32 v[60:61], v[60:61], v[66:67]
	v_mov_b32_e32 v67, v75
	v_mul_f32_e32 v72, v72, v73
	v_mul_f32_e32 v73, v60, v61
	v_pk_mul_f32 v[60:61], v[80:81], v[66:67]
	v_cvt_pk_bf16_f32 v72, v74, v72
	v_mov_b32_e32 v74, v55
	v_mul_f32_e32 v60, v60, v61
	v_cvt_pk_bf16_f32 v73, v73, v60
	s_waitcnt vmcnt(14)
; #define GAS __attribute__((address_space(1)))
; __device__ __forceinline__ unsigned pk2(float lo, float hi) { return pg8::cvt_pk_bf16(lo, hi); }
; __device__ __forceinline__ float siluf_(float x) { return x * sigmoidf_(x); }
; __device__ __forceinline__ void attn_unit(const Args& a, LAS unsigned char* lds, int unit, int tid, int lane, int wave) {
;     ...
; #pragma unroll
;         for (int dt = 0; dt < 8; ++dt) {
;             const int d = 16 * dt + 4 * g;
;             const v2u gw = *(const GAS v2u*)(Z + row * ZLD + ZGA + hq * 128 + d);
;             const float g0 = bflo(gw.x), g1 = bfhi(gw.x), g2 = bflo(gw.y), g3 = bfhi(gw.y);
;             v2u w; w.x = pk2(O[qt][dt][0] * inv * siluf_(g0), O[qt][dt][1] * inv * siluf_(g1)); w.y = pk2(O[qt][dt][2] * inv * siluf_(g2), O[qt][dt][3] * inv * siluf_(g3));
;             *(GAS v2u*)(OAB + row * D + hq * 128 + d) = w;
;         }
	v_mov_b64_e32 v[60:61], v[196:197]
	v_mov_b32_e32 v76, v57
	global_store_dwordx2 v[58:59], v[72:73], off offset:32
	s_nop 0
	v_lshlrev_b32_e32 v67, 16, v60
	v_and_b32_e32 v60, 0xffff0000, v60
	v_mul_f32_e32 v55, 0xbfb8aa3b, v67
	v_lshlrev_b32_e32 v72, 16, v61
	v_and_b32_e32 v61, 0xffff0000, v61
	v_mul_f32_e32 v57, 0xbfb8aa3b, v60
	v_exp_f32_e32 v55, v55
	v_mul_f32_e32 v73, 0xbfb8aa3b, v72
	v_mul_f32_e32 v75, 0xbfb8aa3b, v61
	v_exp_f32_e32 v57, v57
	v_exp_f32_e32 v73, v73
	v_exp_f32_e32 v75, v75
	v_add_f32_e32 v55, 1.0, v55
	v_add_f32_e32 v57, 1.0, v57
	v_rcp_f32_e32 v55, v55
	v_add_f32_e32 v73, 1.0, v73
	v_add_f32_e32 v77, 1.0, v75
	v_rcp_f32_e32 v75, v57
	v_rcp_f32_e32 v57, v73
	v_rcp_f32_e32 v77, v77
	v_pk_mul_f32 v[54:55], v[54:55], v[66:67]
	v_mov_b32_e32 v67, v60
	v_mul_f32_e32 v60, v54, v55
	v_pk_mul_f32 v[54:55], v[74:75], v[66:67]
	v_mov_b32_e32 v67, v72
	v_mul_f32_e32 v72, v54, v55
	v_pk_mul_f32 v[54:55], v[56:57], v[66:67]
	v_mov_b32_e32 v67, v61
	v_mul_f32_e32 v57, v54, v55
	v_pk_mul_f32 v[54:55], v[76:77], v[66:67]
	v_cvt_pk_bf16_f32 v56, v60, v72
	v_mov_b32_e32 v60, v51
	v_mul_f32_e32 v54, v54, v55
	v_cvt_pk_bf16_f32 v57, v57, v54
	s_waitcnt vmcnt(14)
	v_mov_b64_e32 v[54:55], v[198:199]
	v_mov_b32_e32 v72, v53
	global_store_dwordx2 v[58:59], v[56:57], off offset:64
	s_nop 0
	v_lshlrev_b32_e32 v67, 16, v54
	v_and_b32_e32 v54, 0xffff0000, v54
	v_mul_f32_e32 v51, 0xbfb8aa3b, v67
	v_lshlrev_b32_e32 v56, 16, v55
	v_and_b32_e32 v55, 0xffff0000, v55
	v_mul_f32_e32 v53, 0xbfb8aa3b, v54
	v_exp_f32_e32 v51, v51
	v_mul_f32_e32 v57, 0xbfb8aa3b, v56
	v_mul_f32_e32 v61, 0xbfb8aa3b, v55
	v_exp_f32_e32 v53, v53
	v_exp_f32_e32 v57, v57
	v_exp_f32_e32 v61, v61
	v_add_f32_e32 v51, 1.0, v51
	v_add_f32_e32 v53, 1.0, v53
	v_rcp_f32_e32 v51, v51
	v_add_f32_e32 v57, 1.0, v57
	v_add_f32_e32 v73, 1.0, v61
	v_rcp_f32_e32 v61, v53
	v_rcp_f32_e32 v53, v57
	v_rcp_f32_e32 v73, v73
	v_pk_mul_f32 v[50:51], v[50:51], v[66:67]
	v_mov_b32_e32 v67, v54
	v_mul_f32_e32 v54, v50, v51
	v_pk_mul_f32 v[50:51], v[60:61], v[66:67]
	v_mov_b32_e32 v67, v56
	v_mul_f32_e32 v56, v50, v51
	v_pk_mul_f32 v[50:51], v[52:53], v[66:67]
	v_mov_b32_e32 v67, v55
	v_mul_f32_e32 v53, v50, v51
	v_pk_mul_f32 v[50:51], v[72:73], v[66:67]
	v_cvt_pk_bf16_f32 v52, v54, v56
	v_mov_b32_e32 v54, v47
	v_mul_f32_e32 v50, v50, v51
	v_cvt_pk_bf16_f32 v53, v53, v50
	s_waitcnt vmcnt(14)
	v_mov_b64_e32 v[50:51], v[200:201]
	v_mov_b32_e32 v56, v49
	global_store_dwordx2 v[58:59], v[52:53], off offset:96
	s_nop 0
	v_lshlrev_b32_e32 v67, 16, v50
	v_and_b32_e32 v50, 0xffff0000, v50
	v_mul_f32_e32 v47, 0xbfb8aa3b, v67
	v_lshlrev_b32_e32 v52, 16, v51
	v_and_b32_e32 v51, 0xffff0000, v51
	v_mul_f32_e32 v49, 0xbfb8aa3b, v50
	v_exp_f32_e32 v47, v47
	v_mul_f32_e32 v53, 0xbfb8aa3b, v52
	v_mul_f32_e32 v55, 0xbfb8aa3b, v51
	v_exp_f32_e32 v49, v49
	v_exp_f32_e32 v53, v53
	v_exp_f32_e32 v55, v55
	v_add_f32_e32 v47, 1.0, v47
	v_add_f32_e32 v49, 1.0, v49
	v_rcp_f32_e32 v47, v47
	v_add_f32_e32 v53, 1.0, v53
	v_add_f32_e32 v57, 1.0, v55
	v_rcp_f32_e32 v55, v49
	v_rcp_f32_e32 v49, v53
	v_rcp_f32_e32 v57, v57
	v_pk_mul_f32 v[46:47], v[46:47], v[66:67]
	v_mov_b32_e32 v67, v50
	v_mul_f32_e32 v50, v46, v47
	v_pk_mul_f32 v[46:47], v[54:55], v[66:67]
	v_mov_b32_e32 v67, v52
	v_mul_f32_e32 v52, v46, v47
	v_pk_mul_f32 v[46:47], v[48:49], v[66:67]
	v_mov_b32_e32 v67, v51
	v_mul_f32_e32 v49, v46, v47
	v_pk_mul_f32 v[46:47], v[56:57], v[66:67]
	v_cvt_pk_bf16_f32 v48, v50, v52
	v_mov_b32_e32 v50, v43
	v_mul_f32_e32 v46, v46, v47
	v_cvt_pk_bf16_f32 v49, v49, v46
	s_waitcnt vmcnt(14)
	v_mov_b64_e32 v[46:47], v[202:203]
	v_mov_b32_e32 v52, v45
	global_store_dwordx2 v[58:59], v[48:49], off offset:128
	s_nop 0
	v_lshlrev_b32_e32 v67, 16, v46
	v_and_b32_e32 v46, 0xffff0000, v46
	v_mul_f32_e32 v43, 0xbfb8aa3b, v67
	v_lshlrev_b32_e32 v48, 16, v47
	v_and_b32_e32 v47, 0xffff0000, v47
	v_mul_f32_e32 v45, 0xbfb8aa3b, v46
	v_exp_f32_e32 v43, v43
	v_mul_f32_e32 v49, 0xbfb8aa3b, v48
	v_mul_f32_e32 v51, 0xbfb8aa3b, v47
	v_exp_f32_e32 v45, v45
	v_exp_f32_e32 v49, v49
	v_exp_f32_e32 v51, v51
	v_add_f32_e32 v43, 1.0, v43
	v_add_f32_e32 v45, 1.0, v45
	v_rcp_f32_e32 v43, v43
	v_add_f32_e32 v49, 1.0, v49
	v_add_f32_e32 v53, 1.0, v51
	v_rcp_f32_e32 v51, v45
	v_rcp_f32_e32 v45, v49
	v_rcp_f32_e32 v53, v53
	v_pk_mul_f32 v[42:43], v[42:43], v[66:67]
	v_mov_b32_e32 v67, v46
	v_mul_f32_e32 v46, v42, v43
	v_pk_mul_f32 v[42:43], v[50:51], v[66:67]
	v_mov_b32_e32 v67, v48
	v_mul_f32_e32 v48, v42, v43
	v_pk_mul_f32 v[42:43], v[44:45], v[66:67]
	v_mov_b32_e32 v67, v47
	v_mul_f32_e32 v45, v42, v43
	v_pk_mul_f32 v[42:43], v[52:53], v[66:67]
	v_cvt_pk_bf16_f32 v44, v46, v48
	v_mov_b32_e32 v46, v39
	v_mul_f32_e32 v42, v42, v43
	v_cvt_pk_bf16_f32 v45, v45, v42
	s_waitcnt vmcnt(14)
	v_mov_b64_e32 v[42:43], v[204:205]
	v_mov_b32_e32 v48, v41
	global_store_dwordx2 v[58:59], v[44:45], off offset:160
	s_nop 0
	v_lshlrev_b32_e32 v67, 16, v42
	v_and_b32_e32 v42, 0xffff0000, v42
	v_mul_f32_e32 v39, 0xbfb8aa3b, v67
	v_lshlrev_b32_e32 v44, 16, v43
	v_and_b32_e32 v43, 0xffff0000, v43
	v_mul_f32_e32 v41, 0xbfb8aa3b, v42
	v_exp_f32_e32 v39, v39
	v_mul_f32_e32 v45, 0xbfb8aa3b, v44
	v_mul_f32_e32 v47, 0xbfb8aa3b, v43
	v_exp_f32_e32 v41, v41
	v_exp_f32_e32 v45, v45
	v_exp_f32_e32 v47, v47
	v_add_f32_e32 v39, 1.0, v39
	v_add_f32_e32 v41, 1.0, v41
	v_rcp_f32_e32 v39, v39
	v_add_f32_e32 v45, 1.0, v45
	v_add_f32_e32 v49, 1.0, v47
	v_rcp_f32_e32 v47, v41
	v_rcp_f32_e32 v41, v45
	v_rcp_f32_e32 v49, v49
	v_pk_mul_f32 v[38:39], v[38:39], v[66:67]
	v_mov_b32_e32 v67, v42
	v_mul_f32_e32 v42, v38, v39
	v_pk_mul_f32 v[38:39], v[46:47], v[66:67]
	v_mov_b32_e32 v67, v44
	v_mul_f32_e32 v44, v38, v39
	v_pk_mul_f32 v[38:39], v[40:41], v[66:67]
	v_mov_b32_e32 v67, v43
	v_mul_f32_e32 v41, v38, v39
	v_pk_mul_f32 v[38:39], v[48:49], v[66:67]
	v_cvt_pk_bf16_f32 v40, v42, v44
	v_mov_b32_e32 v42, v35
	v_mul_f32_e32 v38, v38, v39
	v_cvt_pk_bf16_f32 v41, v41, v38
	s_waitcnt vmcnt(14)
; #define GAS __attribute__((address_space(1)))
; __device__ __forceinline__ unsigned pk2(float lo, float hi) { return pg8::cvt_pk_bf16(lo, hi); }
; __device__ __forceinline__ float fexp2(float x) { return __builtin_amdgcn_exp2f(x); }
; __device__ __forceinline__ float siluf_(float x) { return x * sigmoidf_(x); }
; __device__ __forceinline__ void attn_unit(const Args& a, LAS unsigned char* lds, int unit, int tid, int lane, int wave) {
;     ...
;     for (int qt = 0; qt < 2; ++qt) {
;         float L = lpart[qt]; L += __shfl_xor(L, 16); L += __shfl_xor(L, 32);
;         L += fexp2(sinkl2 - mrun[qt]);
;         const float inv = 1.0f / L;
;         const size_t row = (size_t)b * SEQ + nblk * 128 + qoff + 16 * qt + c16;
; #pragma unroll
;         for (int dt = 0; dt < 8; ++dt) {
;             const int d = 16 * dt + 4 * g;
;             const v2u gw = *(const GAS v2u*)(Z + row * ZLD + ZGA + hq * 128 + d);
;             const float g0 = bflo(gw.x), g1 = bfhi(gw.x), g2 = bflo(gw.y), g3 = bfhi(gw.y);
;             v2u w; w.x = pk2(O[qt][dt][0] * inv * siluf_(g0), O[qt][dt][1] * inv * siluf_(g1)); w.y = pk2(O[qt][dt][2] * inv * siluf_(g2), O[qt][dt][3] * inv * siluf_(g3));
;             *(GAS v2u*)(OAB + row * D + hq * 128 + d) = w;
;         }
	v_mov_b64_e32 v[38:39], v[206:207]
	v_mov_b32_e32 v44, v37
	global_store_dwordx2 v[58:59], v[40:41], off offset:192
	v_add_co_u32_e32 v46, vcc, s4, v62
	s_mov_b64 s[4:5], 0x6d800
	s_nop 0
	v_addc_co_u32_e32 v47, vcc, 0, v63, vcc
	s_nop 0
	v_lshlrev_b32_e32 v67, 16, v38
	v_and_b32_e32 v38, 0xffff0000, v38
	v_mul_f32_e32 v35, 0xbfb8aa3b, v67
	v_lshlrev_b32_e32 v40, 16, v39
	v_and_b32_e32 v39, 0xffff0000, v39
	v_mul_f32_e32 v37, 0xbfb8aa3b, v38
	v_exp_f32_e32 v35, v35
	v_mul_f32_e32 v41, 0xbfb8aa3b, v40
	v_mul_f32_e32 v43, 0xbfb8aa3b, v39
	v_exp_f32_e32 v37, v37
	v_exp_f32_e32 v41, v41
	v_exp_f32_e32 v43, v43
	v_add_f32_e32 v35, 1.0, v35
	v_add_f32_e32 v37, 1.0, v37
	v_rcp_f32_e32 v35, v35
	v_add_f32_e32 v41, 1.0, v41
	v_add_f32_e32 v45, 1.0, v43
	v_rcp_f32_e32 v43, v37
	v_rcp_f32_e32 v37, v41
	v_rcp_f32_e32 v45, v45
	v_pk_mul_f32 v[34:35], v[34:35], v[66:67]
	v_mov_b32_e32 v67, v38
	v_mul_f32_e32 v38, v34, v35
	v_pk_mul_f32 v[34:35], v[42:43], v[66:67]
	v_mov_b32_e32 v67, v40
	v_mul_f32_e32 v40, v34, v35
	v_pk_mul_f32 v[34:35], v[36:37], v[66:67]
	v_mov_b32_e32 v67, v39
	v_mul_f32_e32 v37, v34, v35
	v_pk_mul_f32 v[34:35], v[44:45], v[66:67]
	v_cvt_pk_bf16_f32 v36, v38, v40
	ds_bpermute_b32 v39, v71, v187
	v_mul_f32_e32 v34, v34, v35
	v_cvt_pk_bf16_f32 v37, v37, v34
	s_waitcnt vmcnt(14)
	v_mov_b64_e32 v[34:35], v[208:209]
	v_mov_b32_e32 v38, v30
	s_waitcnt lgkmcnt(0)
	v_add_f32_e32 v30, v187, v39
	v_mov_b32_e32 v40, v31
	ds_bpermute_b32 v31, v70, v30
	v_sub_f32_e32 v41, v186, v188
	v_mov_b32_e32 v42, v32
	v_exp_f32_e32 v32, v41
	global_store_dwordx2 v[58:59], v[36:37], off offset:224
	s_waitcnt lgkmcnt(0)
	v_add_f32_e32 v30, v30, v31
	v_mov_b32_e32 v44, v33
	v_add_f32_e32 v30, v32, v30
	v_div_scale_f32 v31, s[10:11], v30, v30, 1.0
	v_rcp_f32_e32 v39, v31
	v_div_scale_f32 v41, vcc, 1.0, v30, 1.0
	v_lshl_add_u64 v[32:33], v[62:63], 0, s[4:5]
	v_fma_f32 v43, -v31, v39, 1.0
	v_fmac_f32_e32 v39, v43, v39
	v_mul_f32_e32 v43, v41, v39
	v_fma_f32 v45, -v31, v43, v41
	v_fmac_f32_e32 v43, v45, v39
	v_fma_f32 v31, -v31, v43, v41
	v_div_fmas_f32 v31, v31, v39, v43
	v_div_fixup_f32 v30, v31, v30, 1.0
	s_nop 0
	v_lshlrev_b32_e32 v31, 16, v34
	v_and_b32_e32 v36, 0xffff0000, v34
	v_lshlrev_b32_e32 v37, 16, v35
	v_mul_f32_e32 v34, 0xbfb8aa3b, v31
	v_and_b32_e32 v46, 0xffff0000, v35
	v_mul_f32_e32 v35, 0xbfb8aa3b, v36
	v_mul_f32_e32 v39, 0xbfb8aa3b, v37
	v_exp_f32_e32 v34, v34
	v_mul_f32_e32 v41, 0xbfb8aa3b, v46
	v_exp_f32_e32 v35, v35
	v_exp_f32_e32 v39, v39
	v_exp_f32_e32 v41, v41
	v_add_f32_e32 v34, 1.0, v34
	v_add_f32_e32 v35, 1.0, v35
	v_add_f32_e32 v43, 1.0, v39
	v_rcp_f32_e32 v39, v34
	v_add_f32_e32 v45, 1.0, v41
	v_rcp_f32_e32 v41, v35
	v_rcp_f32_e32 v43, v43
	v_rcp_f32_e32 v45, v45
	v_pk_mul_f32 v[34:35], v[38:39], v[30:31]
	v_mov_b32_e32 v31, v36
	v_mul_f32_e32 v36, v34, v35
	v_pk_mul_f32 v[34:35], v[40:41], v[30:31]
	v_mov_b32_e32 v31, v37
	v_mul_f32_e32 v37, v34, v35
	v_pk_mul_f32 v[34:35], v[42:43], v[30:31]
	v_mov_b32_e32 v31, v46
	v_cvt_pk_bf16_f32 v36, v36, v37
	v_mul_f32_e32 v37, v34, v35
	v_pk_mul_f32 v[34:35], v[44:45], v[30:31]
	v_mov_b32_e32 v38, v26
	v_mul_f32_e32 v31, v34, v35
	v_cvt_pk_bf16_f32 v37, v37, v31
	s_waitcnt vmcnt(14)
	v_mov_b64_e32 v[34:35], v[210:211]
	v_mov_b32_e32 v40, v27
	v_lshl_add_u64 v[26:27], s[0:1], 0, v[64:65]
	v_lshl_add_u64 v[26:27], v[26:27], 0, v[160:161]
	v_mov_b32_e32 v42, v29
	global_store_dwordx2 v[26:27], v[36:37], off
	s_nop 0
	v_lshlrev_b32_e32 v31, 16, v34
	v_and_b32_e32 v36, 0xffff0000, v34
	v_and_b32_e32 v44, 0xffff0000, v35
	v_mul_f32_e32 v29, 0xbfb8aa3b, v31
	v_lshlrev_b32_e32 v37, 16, v35
	v_mul_f32_e32 v34, 0xbfb8aa3b, v36
	v_mul_f32_e32 v39, 0xbfb8aa3b, v44
	v_exp_f32_e32 v29, v29
	v_mul_f32_e32 v35, 0xbfb8aa3b, v37
	v_exp_f32_e32 v34, v34
	v_exp_f32_e32 v39, v39
	v_exp_f32_e32 v35, v35
	v_add_f32_e32 v29, 1.0, v29
	v_add_f32_e32 v34, 1.0, v34
	v_add_f32_e32 v43, 1.0, v39
	v_rcp_f32_e32 v39, v29
	v_add_f32_e32 v35, 1.0, v35
	v_rcp_f32_e32 v41, v34
	v_rcp_f32_e32 v29, v35
	v_rcp_f32_e32 v43, v43
	v_pk_mul_f32 v[34:35], v[38:39], v[30:31]
	v_mov_b32_e32 v31, v36
	v_mul_f32_e32 v36, v34, v35
	v_pk_mul_f32 v[34:35], v[40:41], v[30:31]
	v_mov_b32_e32 v31, v37
	v_pk_mul_f32 v[28:29], v[28:29], v[30:31]
	v_mov_b32_e32 v31, v44
	v_mul_f32_e32 v34, v34, v35
	v_mul_f32_e32 v35, v28, v29
	v_pk_mul_f32 v[28:29], v[42:43], v[30:31]
	v_cvt_pk_bf16_f32 v34, v36, v34
	v_mov_b32_e32 v36, v23
	v_mul_f32_e32 v28, v28, v29
	v_cvt_pk_bf16_f32 v35, v35, v28
	s_waitcnt vmcnt(14)
	v_mov_b64_e32 v[28:29], v[212:213]
	v_mov_b32_e32 v38, v25
	global_store_dwordx2 v[26:27], v[34:35], off offset:32
	s_nop 0
	v_lshlrev_b32_e32 v31, 16, v28
	v_and_b32_e32 v28, 0xffff0000, v28
	v_mul_f32_e32 v23, 0xbfb8aa3b, v31
	v_lshlrev_b32_e32 v34, 16, v29
	v_and_b32_e32 v29, 0xffff0000, v29
	v_mul_f32_e32 v25, 0xbfb8aa3b, v28
	v_exp_f32_e32 v23, v23
	v_mul_f32_e32 v35, 0xbfb8aa3b, v34
	v_mul_f32_e32 v37, 0xbfb8aa3b, v29
	v_exp_f32_e32 v25, v25
	v_exp_f32_e32 v35, v35
	v_exp_f32_e32 v37, v37
	v_add_f32_e32 v23, 1.0, v23
	v_add_f32_e32 v25, 1.0, v25
	v_rcp_f32_e32 v23, v23
	v_add_f32_e32 v35, 1.0, v35
	v_add_f32_e32 v39, 1.0, v37
	v_rcp_f32_e32 v37, v25
	v_rcp_f32_e32 v25, v35
	v_rcp_f32_e32 v39, v39
	v_pk_mul_f32 v[22:23], v[22:23], v[30:31]
	v_mov_b32_e32 v31, v28
	v_mul_f32_e32 v28, v22, v23
	v_pk_mul_f32 v[22:23], v[36:37], v[30:31]
	v_mov_b32_e32 v31, v34
	v_mul_f32_e32 v34, v22, v23
	v_pk_mul_f32 v[22:23], v[24:25], v[30:31]
	v_mov_b32_e32 v31, v29
	v_mul_f32_e32 v25, v22, v23
	v_pk_mul_f32 v[22:23], v[38:39], v[30:31]
	v_cvt_pk_bf16_f32 v24, v28, v34
	v_mov_b32_e32 v28, v19
	v_mul_f32_e32 v22, v22, v23
	v_cvt_pk_bf16_f32 v25, v25, v22
	s_waitcnt vmcnt(14)
; #define GAS __attribute__((address_space(1)))
; __device__ __forceinline__ unsigned pk2(float lo, float hi) { return pg8::cvt_pk_bf16(lo, hi); }
; __device__ __forceinline__ float siluf_(float x) { return x * sigmoidf_(x); }
; __device__ __forceinline__ void attn_unit(const Args& a, LAS unsigned char* lds, int unit, int tid, int lane, int wave) {
;     ...
; #pragma unroll
;         for (int dt = 0; dt < 8; ++dt) {
;             const int d = 16 * dt + 4 * g;
;             const v2u gw = *(const GAS v2u*)(Z + row * ZLD + ZGA + hq * 128 + d);
;             const float g0 = bflo(gw.x), g1 = bfhi(gw.x), g2 = bflo(gw.y), g3 = bfhi(gw.y);
;             v2u w; w.x = pk2(O[qt][dt][0] * inv * siluf_(g0), O[qt][dt][1] * inv * siluf_(g1)); w.y = pk2(O[qt][dt][2] * inv * siluf_(g2), O[qt][dt][3] * inv * siluf_(g3));
;             *(GAS v2u*)(OAB + row * D + hq * 128 + d) = w;
;         }
;     }
	v_mov_b64_e32 v[22:23], v[214:215]
	v_mov_b32_e32 v34, v21
	global_store_dwordx2 v[26:27], v[24:25], off offset:64
	s_nop 0
	v_lshlrev_b32_e32 v31, 16, v22
	v_and_b32_e32 v22, 0xffff0000, v22
	v_mul_f32_e32 v19, 0xbfb8aa3b, v31
	v_lshlrev_b32_e32 v24, 16, v23
	v_and_b32_e32 v23, 0xffff0000, v23
	v_mul_f32_e32 v21, 0xbfb8aa3b, v22
	v_exp_f32_e32 v19, v19
	v_mul_f32_e32 v25, 0xbfb8aa3b, v24
	v_mul_f32_e32 v29, 0xbfb8aa3b, v23
	v_exp_f32_e32 v21, v21
	v_exp_f32_e32 v25, v25
	v_exp_f32_e32 v29, v29
	v_add_f32_e32 v19, 1.0, v19
	v_add_f32_e32 v21, 1.0, v21
	v_rcp_f32_e32 v19, v19
	v_add_f32_e32 v25, 1.0, v25
	v_add_f32_e32 v35, 1.0, v29
	v_rcp_f32_e32 v29, v21
	v_rcp_f32_e32 v21, v25
	v_rcp_f32_e32 v35, v35
	v_pk_mul_f32 v[18:19], v[18:19], v[30:31]
	v_mov_b32_e32 v31, v22
	v_mul_f32_e32 v22, v18, v19
	v_pk_mul_f32 v[18:19], v[28:29], v[30:31]
	v_mov_b32_e32 v31, v24
	v_mul_f32_e32 v24, v18, v19
	v_pk_mul_f32 v[18:19], v[20:21], v[30:31]
	v_mov_b32_e32 v31, v23
	v_mul_f32_e32 v21, v18, v19
	v_pk_mul_f32 v[18:19], v[34:35], v[30:31]
	v_cvt_pk_bf16_f32 v20, v22, v24
	v_mov_b32_e32 v22, v15
	v_mul_f32_e32 v18, v18, v19
	v_cvt_pk_bf16_f32 v21, v21, v18
	s_waitcnt vmcnt(14)
	v_mov_b64_e32 v[18:19], v[216:217]
	v_mov_b32_e32 v24, v17
	global_store_dwordx2 v[26:27], v[20:21], off offset:96
	s_nop 0
	v_lshlrev_b32_e32 v31, 16, v18
	v_and_b32_e32 v18, 0xffff0000, v18
	v_mul_f32_e32 v15, 0xbfb8aa3b, v31
	v_lshlrev_b32_e32 v20, 16, v19
	v_and_b32_e32 v19, 0xffff0000, v19
	v_mul_f32_e32 v17, 0xbfb8aa3b, v18
	v_exp_f32_e32 v15, v15
	v_mul_f32_e32 v21, 0xbfb8aa3b, v20
	v_mul_f32_e32 v23, 0xbfb8aa3b, v19
	v_exp_f32_e32 v17, v17
	v_exp_f32_e32 v21, v21
	v_exp_f32_e32 v23, v23
	v_add_f32_e32 v15, 1.0, v15
	v_add_f32_e32 v17, 1.0, v17
	v_rcp_f32_e32 v15, v15
	v_add_f32_e32 v21, 1.0, v21
	v_add_f32_e32 v25, 1.0, v23
	v_rcp_f32_e32 v23, v17
	v_rcp_f32_e32 v17, v21
	v_rcp_f32_e32 v25, v25
	v_pk_mul_f32 v[14:15], v[14:15], v[30:31]
	v_mov_b32_e32 v31, v18
	v_mul_f32_e32 v18, v14, v15
	v_pk_mul_f32 v[14:15], v[22:23], v[30:31]
	v_mov_b32_e32 v31, v20
	v_mul_f32_e32 v20, v14, v15
	v_pk_mul_f32 v[14:15], v[16:17], v[30:31]
	v_mov_b32_e32 v31, v19
	v_mul_f32_e32 v17, v14, v15
	v_pk_mul_f32 v[14:15], v[24:25], v[30:31]
	v_cvt_pk_bf16_f32 v16, v18, v20
	v_mov_b32_e32 v18, v11
	v_mul_f32_e32 v14, v14, v15
	v_cvt_pk_bf16_f32 v17, v17, v14
	s_waitcnt vmcnt(14)
	v_mov_b64_e32 v[14:15], v[218:219]
	v_mov_b32_e32 v20, v13
	global_store_dwordx2 v[26:27], v[16:17], off offset:128
	s_nop 0
	v_lshlrev_b32_e32 v31, 16, v14
	v_and_b32_e32 v14, 0xffff0000, v14
	v_mul_f32_e32 v11, 0xbfb8aa3b, v31
	v_lshlrev_b32_e32 v16, 16, v15
	v_and_b32_e32 v15, 0xffff0000, v15
	v_mul_f32_e32 v13, 0xbfb8aa3b, v14
	v_exp_f32_e32 v11, v11
	v_mul_f32_e32 v17, 0xbfb8aa3b, v16
	v_mul_f32_e32 v19, 0xbfb8aa3b, v15
	v_exp_f32_e32 v13, v13
	v_exp_f32_e32 v17, v17
	v_exp_f32_e32 v19, v19
	v_add_f32_e32 v11, 1.0, v11
	v_add_f32_e32 v13, 1.0, v13
	v_rcp_f32_e32 v11, v11
	v_add_f32_e32 v17, 1.0, v17
	v_add_f32_e32 v21, 1.0, v19
	v_rcp_f32_e32 v19, v13
	v_rcp_f32_e32 v13, v17
	v_rcp_f32_e32 v21, v21
	v_pk_mul_f32 v[10:11], v[10:11], v[30:31]
	v_mov_b32_e32 v31, v14
	v_mul_f32_e32 v14, v10, v11
	v_pk_mul_f32 v[10:11], v[18:19], v[30:31]
	v_mov_b32_e32 v31, v16
	v_mul_f32_e32 v16, v10, v11
	v_pk_mul_f32 v[10:11], v[12:13], v[30:31]
	v_mov_b32_e32 v31, v15
	v_mul_f32_e32 v13, v10, v11
	v_pk_mul_f32 v[10:11], v[20:21], v[30:31]
	v_cvt_pk_bf16_f32 v12, v14, v16
	v_mov_b32_e32 v14, v7
	v_mul_f32_e32 v10, v10, v11
	v_cvt_pk_bf16_f32 v13, v13, v10
	s_waitcnt vmcnt(14)
	v_mov_b64_e32 v[10:11], v[220:221]
	v_mov_b32_e32 v16, v9
	global_store_dwordx2 v[26:27], v[12:13], off offset:160
	s_nop 0
	v_lshlrev_b32_e32 v31, 16, v10
	v_and_b32_e32 v10, 0xffff0000, v10
	v_mul_f32_e32 v7, 0xbfb8aa3b, v31
	v_lshlrev_b32_e32 v12, 16, v11
	v_and_b32_e32 v11, 0xffff0000, v11
	v_mul_f32_e32 v9, 0xbfb8aa3b, v10
	v_exp_f32_e32 v7, v7
	v_mul_f32_e32 v13, 0xbfb8aa3b, v12
	v_mul_f32_e32 v15, 0xbfb8aa3b, v11
	v_exp_f32_e32 v9, v9
	v_exp_f32_e32 v13, v13
	v_exp_f32_e32 v15, v15
	v_add_f32_e32 v7, 1.0, v7
	v_add_f32_e32 v9, 1.0, v9
	v_rcp_f32_e32 v7, v7
	v_add_f32_e32 v13, 1.0, v13
	v_add_f32_e32 v17, 1.0, v15
	v_rcp_f32_e32 v15, v9
	v_rcp_f32_e32 v9, v13
	v_rcp_f32_e32 v17, v17
	v_pk_mul_f32 v[6:7], v[6:7], v[30:31]
	v_mov_b32_e32 v31, v10
	v_mul_f32_e32 v10, v6, v7
	v_pk_mul_f32 v[6:7], v[14:15], v[30:31]
	v_mov_b32_e32 v31, v12
	v_mul_f32_e32 v12, v6, v7
	v_pk_mul_f32 v[6:7], v[8:9], v[30:31]
	v_mov_b32_e32 v31, v11
	v_mul_f32_e32 v9, v6, v7
	v_pk_mul_f32 v[6:7], v[16:17], v[30:31]
	v_cvt_pk_bf16_f32 v8, v10, v12
	v_mov_b32_e32 v10, v3
	v_mul_f32_e32 v6, v6, v7
	v_cvt_pk_bf16_f32 v9, v9, v6
	s_waitcnt vmcnt(14)
	v_mov_b64_e32 v[6:7], v[222:223]
	v_mov_b32_e32 v12, v5
	global_store_dwordx2 v[26:27], v[8:9], off offset:192
	s_nop 0
	v_lshlrev_b32_e32 v31, 16, v6
	v_and_b32_e32 v6, 0xffff0000, v6
	v_mul_f32_e32 v3, 0xbfb8aa3b, v31
	v_lshlrev_b32_e32 v8, 16, v7
	v_and_b32_e32 v7, 0xffff0000, v7
	v_mul_f32_e32 v5, 0xbfb8aa3b, v6
	v_exp_f32_e32 v3, v3
	v_mul_f32_e32 v9, 0xbfb8aa3b, v8
	v_mul_f32_e32 v11, 0xbfb8aa3b, v7
	v_exp_f32_e32 v5, v5
	v_exp_f32_e32 v9, v9
	v_exp_f32_e32 v11, v11
	v_add_f32_e32 v3, 1.0, v3
	v_add_f32_e32 v5, 1.0, v5
	v_rcp_f32_e32 v3, v3
	v_add_f32_e32 v9, 1.0, v9
	v_add_f32_e32 v13, 1.0, v11
	v_rcp_f32_e32 v11, v5
	v_rcp_f32_e32 v5, v9
	v_rcp_f32_e32 v13, v13
	v_pk_mul_f32 v[2:3], v[2:3], v[30:31]
	v_mov_b32_e32 v31, v6
	v_mul_f32_e32 v6, v2, v3
	v_pk_mul_f32 v[2:3], v[10:11], v[30:31]
	v_mov_b32_e32 v31, v8
	v_mul_f32_e32 v8, v2, v3
	v_pk_mul_f32 v[2:3], v[4:5], v[30:31]
	v_mov_b32_e32 v31, v7
	v_mul_f32_e32 v5, v2, v3
	v_pk_mul_f32 v[2:3], v[12:13], v[30:31]
	v_cvt_pk_bf16_f32 v4, v6, v8
	s_nop 0
	v_mul_f32_e32 v2, v2, v3
	v_cvt_pk_bf16_f32 v5, v5, v2
	global_store_dwordx2 v[26:27], v[4:5], off offset:224
	s_cbranch_scc1 .LBB0_664
